# attention half 1: MFMA-first loop head (no VALU before the first QK MFMA), finishSM work re-cut to roughly equal cost per MFMA gap
# baseline (speedup 1.0000x reference)
; #define LAS __attribute__((address_space(3)))
; template <bool FIRST>
; __device__ __forceinline__ void partialSM(f32x16& p0, f32x16& p1, f32x16& negm, float& dl, float& alpha) {
;     float pmax = p0[0];
; #pragma unroll
;     for (int r = 1; r < 16; ++r) pmax = fmaxf(pmax, p0[r]);
; #pragma unroll
;     for (int r = 0; r < 16; ++r) pmax = fmaxf(pmax, p1[r]);
;     { auto rr = __builtin_amdgcn_permlane32_swap(__float_as_uint(pmax), __float_as_uint(pmax), false, false);
;       pmax = fmaxf(__uint_as_float(rr[0]), __uint_as_float(rr[1])); }
;     if (FIRST) {
;         dl = 0.f; alpha = 1.f; const float d0_ = pmax - SH;
; #pragma unroll
;         for (int r = 0; r < 16; ++r) { p0[r] -= d0_; p1[r] -= d0_; negm[r] -= d0_; }
;     } else {
;         const bool keep = __all(pmax <= SH + THRL);
;         dl = keep ? 0.f : fmaxf(pmax - SH, 0.f); alpha = __builtin_amdgcn_exp2f(-dl);
;     }
; #pragma unroll
;     for (int r = 0; r < 16; ++r) p0[r] = __builtin_amdgcn_exp2f(p0[r]);
; }
; __device__ __forceinline__ void finishSM(f32x16& p0, f32x16& p1, v8i& pa) {
; #pragma unroll
;     for (int r = 0; r < 16; ++r) p1[r] = __builtin_amdgcn_exp2f(p1[r]);
; #pragma unroll
;     for (int w = 0; w < 4; ++w) { pa[w] = (int)pk4_fp8(p0[4 * w], p0[4 * w + 1], p0[4 * w + 2], p0[4 * w + 3]); pa[4 + w] = (int)pk4_fp8(p1[4 * w], p1[4 * w + 1], p1[4 * w + 2], p1[4 * w + 3]); }
; }
; __device__ __forceinline__ v8i ld32(const LAS char* a0, const LAS char* a1) { const v4i x = *(const LAS v4i*)a0, y = *(const LAS v4i*)a1; return (v8i){x[0], x[1], x[2], x[3], y[0], y[1], y[2], y[3]}; }
; __device__ __forceinline__ void qkt(f32x16& p0, f32x16& p1, const LAS char* Ks, int ka0, int ka1, const v8i* qf, const f32x16& negm) {
; #pragma unroll
;     for (int st = 0; st < 3; ++st) {
;         const v8i k0 = ld32(Ks + ka0 + 64 * st, Ks + ka1 + 64 * st), k1 = ld32(Ks + ka0 + 64 * st + 32 * 192, Ks + ka1 + 64 * st + 32 * 192);
;         if (st == 0) { p0 = MFMA8QK(k0, qf[st], negm); p1 = MFMA8QK(k1, qf[st], negm); }
;         else { p0 = MFMA8QK(k0, qf[st], p0); p1 = MFMA8QK(k1, qf[st], p1); } }
; }
; __device__ __forceinline__ void pv_d0(f32x16* o, const LAS char* Vs, int va0, int va1, v8i pa) {
; #pragma unroll
;     for (int d0 = 0; d0 < 4; ++d0) { const v8i vf = ld32(Vs + va0 + 2048 * d0, Vs + va1 + 2048 * d0); o[d0] = MFMA8(pa, vf, o[d0]); }
.LBB0_589:
	s_bitcmp1_b32 s15, 0
	s_cselect_b32 s0, 0x6000, 0
	s_add_i32 s0, s0, 0
	v_add_u32_e32 v0, s0, v244
	v_add_u32_e32 v210, s0, v245
	v_add_u32_e32 v211, 0xf000, v0
	v_add_u32_e32 v212, 0xf000, v210
	ds_read_b128 v[2:5], v0 offset:61504
	ds_read_b128 v[6:9], v210 offset:61504
	s_waitcnt lgkmcnt(4)
	v_mfma_scale_f32_32x32x64_f8f6f4 v[144:159], v[202:209], v[184:191], v[96:111], v234, v233 op_sel_hi:[0,0,0]
	ds_read_b128 v[202:205], v211 offset:6208
	ds_read_b128 v[206:209], v212 offset:6208
	v_exp_f32_e32 v14, v116
	v_exp_f32_e32 v15, v117
	v_exp_f32_e32 v12, v114
	v_exp_f32_e32 v13, v115
	v_exp_f32_e32 v114, v118
	s_waitcnt lgkmcnt(4)
	v_mfma_scale_f32_32x32x64_f8f6f4 v[128:143], v[194:201], v[184:191], v[96:111], v234, v233 op_sel_hi:[0,0,0]
	ds_read_b128 v[194:197], v0 offset:61568
	ds_read_b128 v[198:201], v210 offset:61568
	v_exp_f32_e32 v115, v119
	v_exp_f32_e32 v119, v120
	v_exp_f32_e32 v120, v121
	v_cvt_pk_fp8_f32 v117, v14, v15
	v_exp_f32_e32 v10, v112
	s_waitcnt lgkmcnt(4)
	v_mfma_scale_f32_32x32x64_f8f6f4 v[144:159], v[2:9], v[176:183], v[144:159], v234, v233 op_sel_hi:[0,0,0]
	ds_read_b128 v[2:5], v211 offset:6272
	ds_read_b128 v[6:9], v212 offset:6272
	v_exp_f32_e32 v11, v113
	v_exp_f32_e32 v121, v122
	v_exp_f32_e32 v122, v123
	v_exp_f32_e32 v123, v124
	s_waitcnt lgkmcnt(4)
	v_mfma_scale_f32_32x32x64_f8f6f4 v[128:143], v[202:209], v[176:183], v[128:143], v234, v233 op_sel_hi:[0,0,0]
	v_exp_f32_e32 v124, v125
	v_cvt_pk_fp8_f32 v117, v114, v115 op_sel:[0,0,1]
	v_cvt_pk_fp8_f32 v118, v119, v120
	v_exp_f32_e32 v125, v126
	v_exp_f32_e32 v126, v127
	s_waitcnt lgkmcnt(2)
	v_mfma_scale_f32_32x32x64_f8f6f4 v[144:159], v[194:201], v[168:175], v[144:159], v234, v233 op_sel_hi:[0,0,0]
	v_cvt_pk_fp8_f32 v112, v228, v229
	v_cvt_pk_fp8_f32 v116, v10, v11
	v_cvt_pk_fp8_f32 v113, v226, v227
	v_cvt_pk_fp8_f32 v114, v222, v223
	v_cvt_pk_fp8_f32 v115, v166, v167
	v_cvt_pk_fp8_f32 v119, v123, v124
	v_cvt_pk_fp8_f32 v112, v220, v221 op_sel:[0,0,1]
	v_cvt_pk_fp8_f32 v116, v12, v13 op_sel:[0,0,1]
	v_cvt_pk_fp8_f32 v113, v224, v225 op_sel:[0,0,1]
	s_waitcnt lgkmcnt(0)
	v_mfma_scale_f32_32x32x64_f8f6f4 v[128:143], v[2:9], v[168:175], v[128:143], v234, v233 op_sel_hi:[0,0,0]
	v_cvt_pk_fp8_f32 v114, v162, v163 op_sel:[0,0,1]
	v_cvt_pk_fp8_f32 v118, v121, v122 op_sel:[0,0,1]
	v_cvt_pk_fp8_f32 v115, v164, v165 op_sel:[0,0,1]
	v_cvt_pk_fp8_f32 v119, v125, v126 op_sel:[0,0,1]
	v_mov_b32_e32 v161, v160
	v_mov_b32_e32 v162, v160
	v_mov_b32_e32 v163, v160
	v_mov_b32_e32 v164, v160
	v_mov_b32_e32 v165, v160
	v_mov_b32_e32 v166, v160
	v_mov_b32_e32 v167, v160
	s_add_i32 s66, s21, -2
	s_ashr_i32 s38, s66, 1
	s_mul_hi_i32 s0, s38, 0x55555556
	s_lshr_b32 s1, s0, 31
	s_add_i32 s0, s0, s1
	s_mul_i32 s0, s0, 3
	s_sub_i32 s0, s38, s0
	s_lshl_b32 s0, s0, 14
	s_add_i32 s0, s0, 0
	v_add_u32_e32 v0, s0, v241
	v_add_u32_e32 v11, s0, v240
	ds_read_b128 v[208:211], v0
	ds_read_b128 v[212:215], v11
	ds_read_b128 v[200:203], v0 offset:2048
	ds_read_b128 v[204:207], v11 offset:2048
	ds_read_b128 v[192:195], v0 offset:4096
	ds_read_b128 v[196:199], v11 offset:4096
	ds_read_b128 v[2:5], v0 offset:6144
	ds_read_b128 v[6:9], v11 offset:6144
	v_mov_b32_e32 v125, 0x19000
	v_lshl_add_u32 v126, v216, 4, v125
	v_lshl_add_u32 v127, v216, 2, v125
	ds_read_b128 v[120:123], v126
	ds_read_b32 v124, v127 offset:8192
	v_max_f32_e32 v0, v144, v145
	v_max3_f32 v0, v0, v146, v147
	v_max3_f32 v0, v0, v148, v149
	v_max3_f32 v0, v0, v150, v151
	v_max3_f32 v0, v0, v152, v153
	v_max3_f32 v0, v0, v154, v155
	v_max3_f32 v0, v0, v156, v157
	v_max3_f32 v0, v0, v158, v159
	s_waitcnt lgkmcnt(8)
	v_mfma_scale_f32_32x32x64_f8f6f4 v[64:79], v[112:119], v[208:215], v[64:79], v234, v234 op_sel_hi:[0,0,0]
	v_exp_f32_e32 v14, v144
	v_exp_f32_e32 v15, v145
	v_exp_f32_e32 v10, v148
	v_exp_f32_e32 v11, v149
	v_max3_f32 v0, v0, v128, v129
	v_max3_f32 v0, v0, v130, v131
	v_max3_f32 v0, v0, v132, v133
	v_max3_f32 v0, v0, v134, v135
	s_waitcnt lgkmcnt(6)
	v_mfma_scale_f32_32x32x64_f8f6f4 v[48:63], v[112:119], v[200:207], v[48:63], v234, v234 op_sel_hi:[0,0,0]
	v_exp_f32_e32 v12, v150
	v_exp_f32_e32 v13, v151
	v_max3_f32 v0, v0, v136, v137
	v_max3_f32 v0, v0, v138, v139
	v_max3_f32 v0, v0, v140, v141
	v_max3_f32 v0, v0, v142, v143
	s_waitcnt lgkmcnt(4)
	v_mfma_scale_f32_32x32x64_f8f6f4 v[32:47], v[112:119], v[192:199], v[32:47], v234, v234 op_sel_hi:[0,0,0]
	v_exp_f32_e32 v192, v146
	v_exp_f32_e32 v193, v147
	v_mov_b32_e32 v125, v0
	s_nop 1
	v_permlane32_swap_b32_e32 v0, v125
	s_waitcnt lgkmcnt(2)
	v_mfma_scale_f32_32x32x64_f8f6f4 v[16:31], v[112:119], v[2:9], v[16:31], v234, v234 op_sel_hi:[0,0,0]
	v_exp_f32_e32 v6, v152
	v_exp_f32_e32 v7, v153
	v_exp_f32_e32 v8, v154
	v_exp_f32_e32 v9, v155
	v_mfma_scale_f32_32x32x64_f8f6f4 v[80:95], v[112:119], v[160:167], v[80:95], v234, v234 op_sel_hi:[0,0,0]
	v_exp_f32_e32 v2, v156
	v_exp_f32_e32 v3, v157
	v_exp_f32_e32 v4, v158
	v_exp_f32_e32 v5, v159
	s_waitcnt vmcnt(0) lgkmcnt(0)
	s_barrier
	v_max_f32_e32 v0, v0, v125
	s_add_i32 s42, s38, 2
	v_cmp_ge_f32_e64 s[0:1], s67, v0
	s_cmp_ge_i32 s42, s14
	s_cbranch_scc1 .Lattn_noissue
	s_bitcmp1_b32 s21, 1
	s_cselect_b32 s44, 0x6000, 0
	v_add_u32_e32 v126, s44, v244
	v_add_u32_e32 v127, s44, v245
	ds_read_b128 v[208:211], v126 offset:49152
	ds_read_b128 v[212:215], v127 offset:49152
	s_ashr_i32 s43, s42, 31
	s_mul_i32 s38, s42, 0x18000
	s_mul_hi_i32 s39, s42, 0x18000
	s_add_u32 s38, s24, s38
	s_addc_u32 s39, s25, s39
	s_lshl_b64 s[40:41], s[42:43], 14
	s_add_u32 s40, s52, s40
	s_addc_u32 s41, s53, s41
	s_mul_hi_i32 s43, s42, 0x55555556
	s_lshr_b32 s67, s43, 31
	s_add_i32 s43, s43, s67
	s_mul_i32 s43, s43, 3
	s_sub_i32 s42, s42, s43
	s_lshl_b32 s67, s42, 14
	s_bitcmp1_b32 s66, 1
	s_mov_b32 s42, 0xa000
	s_cselect_b32 s66, 0x10000, s42
	s_and_b64 vcc, exec, s[6:7]
	s_cbranch_vccnz .Lattn_iss_hi
	s_add_i32 m0, s67, s28
	s_nop 0
	global_load_lds_dwordx4 v120, s[40:41]
	s_add_i32 m0, s2, s66
	s_nop 0
	global_load_lds_dwordx4 v121, s[38:39]
	s_add_i32 m0, s27, s66
	s_nop 0
	global_load_lds_dwordx4 v122, s[38:39]
	s_add_i32 m0, s67, s31
	s_nop 0
	global_load_lds_dwordx4 v123, s[40:41]
	s_add_i32 m0, s33, s66
	s_nop 0
	global_load_lds_dwordx4 v124, s[38:39]
	s_branch .Lattn_iss_done
